# E10 + mixer A K tiles staged through wave-private LDS by LDS-DMA (full-row coalesced global reads, XOR swizzle) then ds_read_b128 into the MFMA fragments
# speedup vs baseline: 1.0081x; 1.0081x over previous
; #define LAS __attribute__((address_space(3)))
; __device__ __forceinline__ unsigned cvt_pk_bf16(float lo, float hi) { f32x2_c v = {lo, hi}; bf16x2_c b = __builtin_convertvector(v, bf16x2_c); return __builtin_bit_cast(unsigned, b); }
; __global__ void __launch_bounds__(NWAVES * 64, 2) mk_fwd(Args args) {
;     ...
;                 for (int w2 = 0; w2 < 2; ++w2) { const LA& st = w2 ? sb : sa;
;                     float lt = st.l; { auto rr = __builtin_amdgcn_permlane32_swap(__float_as_uint(lt), __float_as_uint(lt), false, false); lt = __uint_as_float(rr[0]) + __uint_as_float(rr[1]); }
;                     const float inv = __builtin_amdgcn_rcpf(lt); const int rho = tl0 + 32 * w2 + r32;
;                     if (hi == 0) LSE1[rho] = st.m + __builtin_amdgcn_logf(lt);
; #pragma unroll
;                     for (int db = 0; db < 2; ++db)
; #pragma unroll
;                         for (int g = 0; g < 4; ++g) { const f32x16& o = db ? st.o1 : st.o0; u32x2 w; w.x = cvt_pk_bf16(o[4 * g] * inv, o[4 * g + 1] * inv); w.y = cvt_pk_bf16(o[4 * g + 2] * inv, o[4 * g + 3] * inv);
;                             *(LAS u32x2*)(O1 + o1_off(rho, 8 * db + 2 * g + hi)) = w; } }
;             }
;             {
;                 const int q0 = 64 * (v32 * 8 + wave), tqa = q0 + r32, tqb = tqa + 32, kvh = h >> 2;
;                 bf16x8 qa[4], qb[4]; const bf16_t* qp = PROJ + (size_t)tqa * PP + C_QA + h * 64 + 8 * hi;
; #pragma unroll
;                 for (int d0 = 0; d0 < 4; ++d0) { qa[d0] = *(const bf16x8*)(qp + 16 * d0); qb[d0] = *(const bf16x8*)(qp + (size_t)32 * PP + 16 * d0); }
;                 LA sa, sb; sa.o0 = zero16(); sa.o1 = sa.o0; sa.m = NEGBIG; sa.l = 0.f; sb.o0 = zero16(); sb.o1 = sb.o0; sb.m = NEGBIG; sb.l = 0.f;
;                 u32x2 za[8], zb[8]; la_loadz(za, PROJ + (size_t)tqa * PP + C_ZA + h * 64, hi); la_loadz(zb, PROJ + (size_t)tqb * PP + C_ZA + h * 64, hi);
.LBB0_671:
	s_or_b64 exec, exec, s[6:7]
	v_rcp_f32_e32 v34, v33
	v_lshrrev_b32_e32 v33, 1, v32
	v_lshrrev_b32_e32 v35, 4, v32
	v_add_u32_e32 v33, v33, v184
	v_add_lshl_u32 v33, v33, v35, 3
	v_lshl_add_u32 v32, v32, 7, 0
	v_pk_mul_f32 v[0:1], v[34:35], v[0:1] op_sel_hi:[0,1]
	v_pk_mul_f32 v[2:3], v[34:35], v[2:3] op_sel_hi:[0,1]
	v_and_b32_e32 v35, 0x78, v33
	v_cvt_pk_bf16_f32 v0, v0, v1
	v_cvt_pk_bf16_f32 v1, v2, v3
	v_add_u32_e32 v2, v32, v35
	ds_write_b64 v2, v[0:1] offset:36864
	v_pk_mul_f32 v[0:1], v[34:35], v[4:5] op_sel_hi:[0,1]
	v_pk_mul_f32 v[2:3], v[34:35], v[6:7] op_sel_hi:[0,1]
	v_cvt_pk_bf16_f32 v0, v0, v1
	v_cvt_pk_bf16_f32 v1, v2, v3
	v_add_u32_e32 v2, 16, v33
	v_and_b32_e32 v2, 0x78, v2
	v_add_u32_e32 v2, v32, v2
	ds_write_b64 v2, v[0:1] offset:36864
	v_pk_mul_f32 v[0:1], v[34:35], v[8:9] op_sel_hi:[0,1]
	v_pk_mul_f32 v[2:3], v[34:35], v[10:11] op_sel_hi:[0,1]
	v_cvt_pk_bf16_f32 v0, v0, v1
	v_cvt_pk_bf16_f32 v1, v2, v3
	v_add_u32_e32 v2, 32, v33
	v_and_b32_e32 v2, 0x78, v2
	v_add_u32_e32 v2, v32, v2
	ds_write_b64 v2, v[0:1] offset:36864
	v_pk_mul_f32 v[0:1], v[34:35], v[12:13] op_sel_hi:[0,1]
	v_pk_mul_f32 v[2:3], v[34:35], v[14:15] op_sel_hi:[0,1]
	v_cvt_pk_bf16_f32 v0, v0, v1
	v_cvt_pk_bf16_f32 v1, v2, v3
	v_add_u32_e32 v2, 48, v33
	v_and_b32_e32 v2, 0x78, v2
	v_add_u32_e32 v2, v32, v2
	ds_write_b64 v2, v[0:1] offset:36864
	v_pk_mul_f32 v[0:1], v[34:35], v[16:17] op_sel_hi:[0,1]
	v_pk_mul_f32 v[2:3], v[34:35], v[18:19] op_sel_hi:[0,1]
	v_cvt_pk_bf16_f32 v0, v0, v1
	v_cvt_pk_bf16_f32 v1, v2, v3
	v_xad_u32 v2, v35, 64, v32
	ds_write_b64 v2, v[0:1] offset:36864
	v_pk_mul_f32 v[0:1], v[34:35], v[20:21] op_sel_hi:[0,1]
	v_pk_mul_f32 v[2:3], v[34:35], v[22:23] op_sel_hi:[0,1]
	v_cvt_pk_bf16_f32 v0, v0, v1
	v_cvt_pk_bf16_f32 v1, v2, v3
	v_add_u32_e32 v2, 0x50, v33
	v_and_b32_e32 v2, 0x78, v2
	v_add_u32_e32 v2, v32, v2
	ds_write_b64 v2, v[0:1] offset:36864
	v_pk_mul_f32 v[0:1], v[34:35], v[24:25] op_sel_hi:[0,1]
	v_pk_mul_f32 v[2:3], v[34:35], v[26:27] op_sel_hi:[0,1]
	v_cvt_pk_bf16_f32 v0, v0, v1
	v_cvt_pk_bf16_f32 v1, v2, v3
	v_add_u32_e32 v2, 0x60, v33
	v_and_b32_e32 v2, 0x78, v2
	v_add_u32_e32 v2, v32, v2
	s_add_u32 s6, s34, 0x1a400000
	ds_write_b64 v2, v[0:1] offset:36864
	v_pk_mul_f32 v[0:1], v[34:35], v[28:29] op_sel_hi:[0,1]
	v_pk_mul_f32 v[2:3], v[34:35], v[30:31] op_sel_hi:[0,1]
	s_addc_u32 s7, s35, 0
	s_ashr_i32 s40, s58, 6
	v_cvt_pk_bf16_f32 v0, v0, v1
	v_cvt_pk_bf16_f32 v1, v2, v3
	v_add_u32_e32 v2, 0x70, v33
	s_lshl_b32 s10, s0, 3
	v_and_b32_e32 v2, 0x78, v2
	s_add_i32 s8, s10, s40
	v_add_u32_e32 v2, v32, v2
	s_lshl_b32 s11, s8, 6
	ds_write_b64 v2, v[0:1] offset:36864
	v_or_b32_e32 v182, s11, v186
	v_mov_b64_e32 v[2:3], s[74:75]
	v_mad_i64_i32 v[0:1], s[8:9], v182, s64, v[2:3]
	s_lshl_b64 s[70:71], s[30:31], 1
	v_lshl_add_u64 v[4:5], v[0:1], 0, s[70:71]
	v_lshlrev_b32_e32 v188, 1, v146
	v_lshl_add_u64 v[0:1], v[4:5], 0, v[188:189]
	s_mov_b32 s8, 0x69000
	v_or_b32_e32 v164, 32, v182
	v_add_co_u32_e32 v6, vcc, s8, v0
	v_mad_i64_i32 v[2:3], s[8:9], v164, s64, v[2:3]
	s_ashr_i32 s8, s37, 1
	s_andn2_b32 s8, s8, 63
	s_add_i32 s9, s8, 0x200
	v_mov_b32_e32 v147, v189
	v_lshl_add_u64 v[2:3], v[2:3], 0, s[70:71]
	v_or_b32_e32 v192, s9, v146
	s_add_i32 s9, s11, 0xffffff80
	v_lshl_add_u64 v[4:5], v[4:5], 0, v[146:147]
	v_lshl_add_u64 v[2:3], v[2:3], 0, v[146:147]
	s_cmpk_lt_u32 s9, 0x4000
	v_addc_co_u32_e32 v7, vcc, 0, v1, vcc
	global_load_dwordx4 v[80:83], v[0:1], off
	global_load_dwordx4 v[84:87], v[0:1], off offset:32
	global_load_dwordx4 v[88:91], v[6:7], off
	global_load_dwordx4 v[92:95], v[6:7], off offset:32
	global_load_dwordx4 v[96:99], v[0:1], off offset:64
	global_load_dwordx4 v[100:103], v[0:1], off offset:96
	global_load_dwordx4 v[104:107], v[6:7], off offset:64
	global_load_dwordx4 v[108:111], v[6:7], off offset:96
	v_mov_b32 v32, 0
	v_mov_b32 v0, 0
	global_load_dwordx2 v[144:145], v[4:5], off offset:1536
	global_load_dwordx2 v[178:179], v[4:5], off offset:1552
; #define LAS __attribute__((address_space(3)))
; __host__ __device__ __forceinline__ int vt_off(int d, int p) { return (d >> 1) * VTPP + (p >> 5) * 64 + (d & 1) * 32 + (p & 31); }
; #define LA_RUN2(NT, TILE, MB, V1, KB, VS_) do { Frag f_; { const TP t0_ = TILE(0); la_loadK(f_, KB, t0_); (VS_).template load<V1>(f_, t0_.voff); } \
;     _Pragma("unroll 1") for (int i_ = 0; i_ < (NT); ++i_) { const TP t_ = TILE(i_); const TP n_ = TILE(i_ + 1 < (NT) ? i_ + 1 : i_); la_step2<MB, V1>(sa, sb, qa, qb, f_, KB, VS_, t_, n_); } } while (0)
; __device__ __forceinline__ void la_loadK(Frag& f, const char* kb, const TP& t) {
; #pragma unroll
;     for (int d0 = 0; d0 < 4; ++d0) f.k[d0] = *(const bf16x8*)(kb + t.koff + d0 * 32);
; __global__ void __launch_bounds__(NWAVES * 64, 2) mk_fwd(Args args) {
;     ...
;                 for (int d0 = 0; d0 < 4; ++d0) { qa[d0] = *(const bf16x8*)(qp + 16 * d0); qb[d0] = *(const bf16x8*)(qp + (size_t)32 * PP + 16 * d0); }
;                 LA sa, sb; sa.o0 = zero16(); sa.o1 = sa.o0; sa.m = NEGBIG; sa.l = 0.f; sb.o0 = zero16(); sb.o1 = sb.o0; sb.m = NEGBIG; sb.l = 0.f;
;                 u32x2 za[8], zb[8]; la_loadz(za, PROJ + (size_t)tqa * PP + C_ZA + h * 64, hi); la_loadz(zb, PROJ + (size_t)tqb * PP + C_ZA + h * 64, hi);
;                 const int vd = kvh * 64 + r32; const unsigned kc = (unsigned)(C_KA + kvh * 64 + 8 * hi);
;                 const VSG vs{(const char*)VTA};
;                 auto tile = [&](int i) -> TP { const int t0r = q0 - 128 + 32 * i; const bool ok = t0r >= 0 && t0r < SEQ; const int t0 = ok ? t0r : q0; TP t;
;                     t.koff = ((unsigned)(t0 + lam) * PP + kc) * 2u; t.voff = (unsigned)(vt_off(vd, t0 + 8 * hi) * 2);
;                     t.tp = (ok && i <= 8) ? (const LAS char*)(tabA + (TABA_C + t0 + 8 * hi - tqa)) : negp;
;                     t.tp2 = (ok && i >= 1) ? (const LAS char*)(tabA + (TABA_C + t0 + 8 * hi - tqb)) : negp; t.cb = 0; return t; };
;                 LA_RUN2(10, tile, MB_A, 32, PB, vs);
	global_load_dwordx2 v[176:177], v[4:5], off offset:1568
	global_load_dwordx2 v[174:175], v[4:5], off offset:1584
	global_load_dwordx2 v[172:173], v[4:5], off offset:1600
	global_load_dwordx2 v[170:171], v[4:5], off offset:1616
	global_load_dwordx2 v[168:169], v[4:5], off offset:1632
	global_load_dwordx2 v[166:167], v[4:5], off offset:1648
	global_load_dwordx2 v[162:163], v[2:3], off offset:1536
	global_load_dwordx2 v[160:161], v[2:3], off offset:1552
	global_load_dwordx2 v[158:159], v[2:3], off offset:1568
	global_load_dwordx2 v[156:157], v[2:3], off offset:1584
	global_load_dwordx2 v[154:155], v[2:3], off offset:1600
	global_load_dwordx2 v[152:153], v[2:3], off offset:1616
	global_load_dwordx2 v[150:151], v[2:3], off offset:1632
	global_load_dwordx2 v[148:149], v[2:3], off offset:1648
	s_cselect_b32 s9, s9, s11
	v_or_b32_e32 v1, s9, v185
	v_mul_lo_u32 v1, v1, s67
	v_add_lshl_u32 v1, v1, v192, 1
	s_lshr_b32 s99, s69, 6
	s_lshl_b32 s98, s99, 12
	s_add_i32 s98, s98, 0x19800
	s_cmp_gt_u32 s99, 5
	s_cselect_b32 s99, 0xc00, 0
	s_add_i32 s99, s98, s99
	v_lshrrev_b32_e32 v240, 3, v252
	v_mul_u32_u24_e32 v240, 0x3480, v240
	v_sub_u32_e32 v241, v192, v146
	v_lshl_add_u32 v240, v241, 1, v240
	v_lshrrev_b32_e32 v241, 4, v252
	v_xor_b32_e32 v241, v241, v252
	v_and_b32_e32 v241, 7, v241
	v_lshl_add_u32 v234, v241, 4, v240
	v_xor_b32_e32 v235, 64, v234
	v_lshrrev_b32_e32 v240, 1, v185
	v_and_b32_e32 v240, 7, v240
	v_lshrrev_b32_e32 v241, 3, v146
	v_xor_b32_e32 v240, v240, v241
	v_lshlrev_b32_e32 v240, 4, v240
	v_lshl_add_u32 v240, v185, 7, v240
	v_add_u32_e32 v236, s99, v240
	v_xor_b32_e32 v237, 32, v236
	v_xor_b32_e32 v238, 64, v236
	v_xor_b32_e32 v239, 0x60, v236
	s_mul_i32 s98, s9, 0x3480
	s_add_i32 m0, s99, 0x0
	v_add_u32_e32 v240, s98, v234
	global_load_lds_dwordx4 v240, s[74:75]
	s_add_i32 m0, s99, 0x400
	s_add_i32 s100, s98, 0x1a400
	v_add_u32_e32 v240, s100, v235
	global_load_lds_dwordx4 v240, s[74:75]
	s_add_i32 m0, s99, 0x800
	s_add_i32 s100, s98, 0x34800
	v_add_u32_e32 v240, s100, v234
	global_load_lds_dwordx4 v240, s[74:75]
	s_add_i32 m0, s99, 0xc00
	s_add_i32 s100, s98, 0x4ec00
	v_add_u32_e32 v240, s100, v235
	global_load_lds_dwordx4 v240, s[74:75]
	v_or_b32_e32 v16, s8, v186
	v_lshrrev_b32_e32 v16, 1, v16
	v_mul_lo_u32 v16, v16, s65
	v_lshlrev_b32_e32 v18, 5, v186
	v_mov_b32_e32 v46, v32
	v_mov_b32_e32 v47, v32
	v_mov_b32_e32 v14, v0
	v_mov_b32_e32 v15, v0
	v_lshl_add_u32 v17, s9, 1, v16
	v_and_b32_e32 v147, 32, v18
	v_mov_b32_e32 v33, v32
	v_mov_b32_e32 v34, v32
	v_mov_b32_e32 v35, v32
	v_mov_b32_e32 v36, v32
	v_mov_b32_e32 v37, v32
	v_mov_b32_e32 v38, v32
	v_mov_b32_e32 v39, v32
	v_mov_b32_e32 v40, v32
	v_mov_b32_e32 v41, v32
	v_mov_b32_e32 v42, v32
	v_mov_b32_e32 v43, v32
	v_mov_b32_e32 v44, v32
	v_mov_b32_e32 v45, v32
	v_mov_b32_e32 v1, v0
	v_mov_b32_e32 v2, v0
	v_mov_b32_e32 v3, v0
	v_mov_b32_e32 v4, v0
	v_mov_b32_e32 v5, v0
	v_mov_b32_e32 v6, v0
	v_mov_b32_e32 v7, v0
	v_mov_b32_e32 v8, v0
	v_mov_b32_e32 v9, v0
	v_mov_b32_e32 v10, v0
	v_mov_b32_e32 v11, v0
	v_mov_b32_e32 v12, v0
	v_mov_b32_e32 v13, v0
	v_or3_b32 v73, v17, v147, v146
	v_or3_b32 v194, v16, v147, v146
	v_mov_b64_e32 v[62:63], v[46:47]
	v_mov_b64_e32 v[30:31], v[14:15]
	v_ashrrev_i32_e32 v183, 31, v182
	s_mov_b32 s12, 0
	v_lshlrev_b32_e32 v180, 2, v184
	v_ashrrev_i32_e32 v165, 31, v164
	s_movk_i32 s13, 0xff80
	v_add_u32_e32 v195, 0, v190
	v_mov_b32_e32 v196, 0xf149f2ca
	v_mov_b32_e32 v193, 0
	v_mov_b64_e32 v[60:61], v[44:45]
	v_mov_b64_e32 v[58:59], v[42:43]
	v_mov_b64_e32 v[56:57], v[40:41]
	v_mov_b64_e32 v[54:55], v[38:39]
	v_mov_b64_e32 v[52:53], v[36:37]
	v_mov_b64_e32 v[50:51], v[34:35]
	v_mov_b64_e32 v[48:49], v[32:33]
	v_mov_b32_e32 v190, 0
	v_mov_b32_e32 v191, 0xf149f2ca
	v_mov_b64_e32 v[28:29], v[12:13]
	v_mov_b64_e32 v[26:27], v[10:11]
	v_mov_b64_e32 v[24:25], v[8:9]
	v_mov_b64_e32 v[22:23], v[6:7]
	v_mov_b64_e32 v[20:21], v[4:5]
	v_mov_b64_e32 v[18:19], v[2:3]
	v_mov_b64_e32 v[16:17], v[0:1]
	s_branch .LBB0_673

; template <class MB> __device__ __forceinline__ void la_soft(LA& st, f32x16& s, const TP& t, bf16x8& pf0, bf16x8& pf1) {
;     float mx = NEGBIG;
; #pragma unroll
;     for (int r = 0; r < 16; ++r) { s[r] = MB::apply(t, r, s[r]); mx = __builtin_fmaxf(mx, s[r]); }
;     { auto rr = __builtin_amdgcn_permlane32_swap(__float_as_uint(mx), __float_as_uint(mx), false, false); mx = __builtin_fmaxf(__uint_as_float(rr[0]), __uint_as_float(rr[1])); }
;     if (__any(mx > st.m)) { const float mn = __builtin_fmaxf(st.m, mx), alpha = __builtin_amdgcn_exp2f(st.m - mn); st.m = mn; st.l *= alpha; st.o0 *= alpha; st.o1 *= alpha; }
; template <class MB, int V1, class VS> __device__ __forceinline__ void la_step2(LA& sa, LA& sb, const bf16x8 (&qa)[4], const bf16x8 (&qb)[4], Frag& f, const char* kb, const VS& vs, const TP& t, const TP& n) {
;     bf16x8 pa0, pa1;
;     { f32x16 s0 = zero16();
; #pragma unroll
;       for (int d0 = 0; d0 < 4; ++d0) s0 = __builtin_amdgcn_mfma_f32_32x32x16_bf16(f.k[d0], qa[d0], s0, 0, 0, 0);
;       la_soft<MB>(sa, s0, t, pa0, pa1); }
.LBB0_673:
	v_lshlrev_b32_e32 v64, 1, v73
	v_ashrrev_i32_e32 v65, 31, v64
	v_lshl_add_u64 v[64:65], s[6:7], 0, v[64:65]
	v_add_co_u32_e32 v66, vcc, s80, v64
	s_add_i32 s8, s11, s13
	s_nop 0
	v_addc_co_u32_e32 v67, vcc, 0, v65, vcc
	global_load_dwordx4 v[128:131], v[66:67], off offset:2080
	global_load_dwordx4 v[136:139], v[66:67], off offset:2048
	global_load_dwordx4 v[132:135], v[64:65], off offset:32
	global_load_dwordx4 v[140:143], v[64:65], off
	s_cmpk_lt_u32 s8, 0x4000
	s_cselect_b64 s[8:9], -1, 0
	s_cmpk_lg_i32 s12, 0x480
	s_cselect_b64 s[14:15], -1, 0
	v_add_u32_e32 v197, s12, v195
	s_and_b64 vcc, s[14:15], s[8:9]
	v_add_u32_e32 v64, 0x80, v197
	v_mov_b32_e32 v65, s53
	v_cndmask_b32_e32 v212, v65, v64, vcc
	v_mov_b32 v64, 0
	ds_read2_b32 v[200:201], v212 offset1:1
	v_mov_b32_e32 v65, v64
	v_mov_b32_e32 v66, v64
	v_mov_b32_e32 v67, v64
	v_mov_b32_e32 v68, v64
	v_mov_b32_e32 v69, v64
	v_mov_b32_e32 v70, v64
	v_mov_b32_e32 v71, v64
	v_mov_b32_e32 v72, v64
	v_mov_b32_e32 v73, v64
	v_mov_b32_e32 v74, v64
	v_mov_b32_e32 v75, v64
	v_mov_b32_e32 v76, v64
	v_mov_b32_e32 v77, v64
	v_mov_b32_e32 v78, v64
	v_mov_b32_e32 v79, v64
	s_waitcnt vmcnt(4)
	ds_read_b128 v[124:127], v236
	ds_read_b128 v[120:123], v237
	ds_read_b128 v[116:119], v238
	ds_read_b128 v[112:115], v239
	s_waitcnt lgkmcnt(0)
	s_nop 0
	v_mfma_f32_32x32x16_bf16 v[64:79], v[124:127], v[80:83], v[64:79]
	s_waitcnt vmcnt(6)
	v_mfma_f32_32x32x16_bf16 v[64:79], v[120:123], v[84:87], v[64:79]
	s_waitcnt vmcnt(5)
	v_mfma_f32_32x32x16_bf16 v[64:79], v[116:119], v[96:99], v[64:79]
	s_waitcnt vmcnt(4)
	v_mfma_f32_32x32x16_bf16 v[64:79], v[112:115], v[100:103], v[64:79]
	s_waitcnt lgkmcnt(0)
	s_nop 10
	v_add_f32_e32 v199, v64, v200
	v_add_f32_e32 v198, v65, v201
	ds_read2_b32 v[64:65], v212 offset0:2 offset1:3
	v_max3_f32 v202, v199, s2, v198
	s_waitcnt lgkmcnt(0)
	v_add_f32_e32 v201, v66, v64
	v_add_f32_e32 v200, v67, v65
	ds_read2_b32 v[64:65], v212 offset0:4 offset1:5
	v_max3_f32 v66, v202, v201, v200
	s_waitcnt lgkmcnt(0)
	v_add_f32_e32 v203, v68, v64
	v_add_f32_e32 v202, v69, v65
	ds_read2_b32 v[64:65], v212 offset0:6 offset1:7
	v_max3_f32 v66, v66, v203, v202
	s_waitcnt lgkmcnt(0)
	v_add_f32_e32 v205, v70, v64
	v_add_f32_e32 v204, v71, v65
	ds_read2_b32 v[64:65], v212 offset0:16 offset1:17
	v_max3_f32 v66, v66, v205, v204
	s_waitcnt lgkmcnt(0)
	v_add_f32_e32 v207, v72, v64
	v_add_f32_e32 v206, v73, v65
	ds_read2_b32 v[64:65], v212 offset0:18 offset1:19
	v_max3_f32 v66, v66, v207, v206
	s_waitcnt lgkmcnt(0)
	v_add_f32_e32 v211, v74, v64
	v_add_f32_e32 v210, v75, v65
	ds_read2_b32 v[64:65], v212 offset0:20 offset1:21
	v_max3_f32 v66, v66, v211, v210
	s_waitcnt lgkmcnt(0)
	v_add_f32_e32 v209, v76, v64
	v_add_f32_e32 v208, v77, v65
	ds_read2_b32 v[64:65], v212 offset0:22 offset1:23
	v_max3_f32 v66, v66, v209, v208
	s_waitcnt lgkmcnt(0)
	v_add_f32_e32 v213, v78, v64
	v_add_f32_e32 v212, v79, v65
	v_max3_f32 v64, v66, v213, v212
	v_mov_b32_e32 v65, v64
	s_nop 1
	v_permlane32_swap_b32_e32 v64, v65
	v_max_f32_e32 v65, v65, v65
	v_max_f32_e32 v64, v64, v64
	v_max_f32_e32 v64, v64, v65
	v_cmp_gt_f32_e32 vcc, v64, v196
	s_cbranch_vccz .LBB0_675
	v_max_f32_e32 v64, v64, v64
	v_max_f32_e32 v65, v196, v196
	v_max_f32_e32 v65, v65, v64
	v_sub_f32_e32 v64, v196, v65
	v_exp_f32_e32 v64, v64
	v_mov_b32_e32 v196, v65
	v_mul_f32_e32 v193, v193, v64
	v_pk_mul_f32 v[62:63], v[62:63], v[64:65] op_sel_hi:[1,0]
	v_pk_mul_f32 v[60:61], v[60:61], v[64:65] op_sel_hi:[1,0]
	v_pk_mul_f32 v[58:59], v[58:59], v[64:65] op_sel_hi:[1,0]
	v_pk_mul_f32 v[56:57], v[56:57], v[64:65] op_sel_hi:[1,0]
	v_pk_mul_f32 v[54:55], v[54:55], v[64:65] op_sel_hi:[1,0]
	v_pk_mul_f32 v[52:53], v[52:53], v[64:65] op_sel_hi:[1,0]
	v_pk_mul_f32 v[50:51], v[50:51], v[64:65] op_sel_hi:[1,0]
	v_pk_mul_f32 v[48:49], v[48:49], v[64:65] op_sel_hi:[1,0]
	v_pk_mul_f32 v[46:47], v[46:47], v[64:65] op_sel_hi:[1,0]
	v_pk_mul_f32 v[44:45], v[44:45], v[64:65] op_sel_hi:[1,0]
	v_pk_mul_f32 v[42:43], v[42:43], v[64:65] op_sel_hi:[1,0]
	v_pk_mul_f32 v[40:41], v[40:41], v[64:65] op_sel_hi:[1,0]
	v_pk_mul_f32 v[38:39], v[38:39], v[64:65] op_sel_hi:[1,0]
	v_pk_mul_f32 v[36:37], v[36:37], v[64:65] op_sel_hi:[1,0]
	v_pk_mul_f32 v[34:35], v[34:35], v[64:65] op_sel_hi:[1,0]
	v_pk_mul_f32 v[32:33], v[32:33], v[64:65] op_sel_hi:[1,0]
; __device__ __forceinline__ void la_loadK(Frag& f, const char* kb, const TP& t) {
; #pragma unroll
;     for (int d0 = 0; d0 < 4; ++d0) f.k[d0] = *(const bf16x8*)(kb + t.koff + d0 * 32);
; template <class MB, int V1, class VS> __device__ __forceinline__ void la_step2(LA& sa, LA& sb, const bf16x8 (&qa)[4], const bf16x8 (&qb)[4], Frag& f, const char* kb, const VS& vs, const TP& t, const TP& n) {
;     ...
;     f32x16 s1 = zero16();
; #pragma unroll
;     for (int d0 = 0; d0 < 4; ++d0) s1 = __builtin_amdgcn_mfma_f32_32x32x16_bf16(f.k[d0], qb[d0], s1, 0, 0, 0);
;     la_loadK(f, kb, n);
;     sa.o0 = __builtin_amdgcn_mfma_f32_32x32x16_bf16(f.v[0], pa0, sa.o0, 0, 0, 0); sa.o1 = __builtin_amdgcn_mfma_f32_32x32x16_bf16(f.v[2], pa0, sa.o1, 0, 0, 0);
;     sa.o0 = __builtin_amdgcn_mfma_f32_32x32x16_bf16(f.v[1], pa1, sa.o0, 0, 0, 0); sa.o1 = __builtin_amdgcn_mfma_f32_32x32x16_bf16(f.v[3], pa1, sa.o1, 0, 0, 0);
;     { bf16x8 pb0, pb1; const TP tb = MB::second(t);
;       la_soft<MB>(sb, s1, tb, pb0, pb1);
.LBB0_675:
	s_cmp_lg_u32 s12, 0
	s_cselect_b64 s[14:15], -1, 0
	s_and_b64 vcc, s[14:15], s[8:9]
	s_add_i32 s13, s13, 32
	s_cmpk_lg_i32 s12, 0x480
	s_cselect_b32 s8, s13, 0xa0
	s_add_i32 s8, s8, s11
	s_cmpk_lt_u32 s8, 0x4000
	s_cselect_b32 s8, s8, s11
	v_or_b32_e32 v64, s8, v185
	v_mul_lo_u32 v64, v64, s67
	v_add_lshl_u32 v219, v64, v192, 1
	v_mov_b32 v64, 0
	v_mov_b32_e32 v218, s53
	v_mov_b32_e32 v65, v64
	v_mov_b32_e32 v66, v64
	v_mov_b32_e32 v67, v64
	v_mov_b32_e32 v68, v64
	v_mov_b32_e32 v69, v64
	v_mov_b32_e32 v70, v64
	v_mov_b32_e32 v71, v64
	v_mov_b32_e32 v72, v64
	v_mov_b32_e32 v73, v64
	v_mov_b32_e32 v74, v64
	v_mov_b32_e32 v75, v64
	v_mov_b32_e32 v76, v64
	v_mov_b32_e32 v77, v64
	v_mov_b32_e32 v78, v64
	v_mov_b32_e32 v79, v64
	v_cndmask_b32_e32 v226, v218, v197, vcc
	s_nop 0
	v_mfma_f32_32x32x16_bf16 v[64:79], v[124:127], v[88:91], v[64:79]
	v_sub_f32_e32 v124, v199, v196
	v_exp_f32_e32 v199, v124
	v_sub_f32_e32 v124, v198, v196
	v_exp_f32_e32 v198, v124
	v_sub_f32_e32 v124, v201, v196
	v_exp_f32_e32 v201, v124
	v_sub_f32_e32 v124, v200, v196
	v_mfma_f32_32x32x16_bf16 v[64:79], v[120:123], v[92:95], v[64:79]
	v_sub_f32_e32 v120, v203, v196
	v_exp_f32_e32 v203, v120
	v_sub_f32_e32 v120, v202, v196
	v_exp_f32_e32 v202, v120
	v_sub_f32_e32 v120, v205, v196
	v_exp_f32_e32 v200, v124
	v_exp_f32_e32 v205, v120
	v_mfma_f32_32x32x16_bf16 v[64:79], v[116:119], v[104:107], v[64:79]
	v_sub_f32_e32 v116, v204, v196
	v_exp_f32_e32 v204, v116
	v_sub_f32_e32 v116, v207, v196
	v_exp_f32_e32 v207, v116
	v_sub_f32_e32 v116, v206, v196
	v_exp_f32_e32 v206, v116
	v_sub_f32_e32 v116, v211, v196
	v_exp_f32_e32 v211, v116
	v_sub_f32_e32 v116, v209, v196
	v_exp_f32_e32 v209, v116
	v_sub_f32_e32 v116, v208, v196
	v_mfma_f32_32x32x16_bf16 v[64:79], v[112:115], v[108:111], v[64:79]
	v_sub_f32_e32 v112, v210, v196
	v_exp_f32_e32 v208, v116
	v_sub_f32_e32 v116, v213, v196
	v_exp_f32_e32 v210, v112
	v_cvt_pk_bf16_f32 v112, v199, v198
	v_cvt_pk_bf16_f32 v113, v201, v200
	v_cvt_pk_bf16_f32 v114, v203, v202
	v_cvt_pk_bf16_f32 v115, v205, v204
	v_exp_f32_e32 v213, v116
	v_sub_f32_e32 v116, v212, v196
	s_waitcnt vmcnt(0)
	v_mfma_f32_32x32x16_bf16 v[48:63], v[140:143], v[112:115], v[48:63]
	v_exp_f32_e32 v212, v116
	s_mul_i32 s98, s8, 0x3480
	s_add_i32 m0, s99, 0x0
	v_add_u32_e32 v240, s98, v234
	global_load_lds_dwordx4 v240, s[74:75]
	s_add_i32 m0, s99, 0x400
	s_add_i32 s100, s98, 0x1a400
	v_add_u32_e32 v240, s100, v235
	global_load_lds_dwordx4 v240, s[74:75]
	v_cvt_pk_bf16_f32 v214, v207, v206
	v_cvt_pk_bf16_f32 v215, v211, v210
	v_cvt_pk_bf16_f32 v216, v209, v208
	v_cvt_pk_bf16_f32 v217, v213, v212
	v_mfma_f32_32x32x16_bf16 v[32:47], v[136:139], v[112:115], v[32:47]
	s_add_i32 m0, s99, 0x800
	s_add_i32 s100, s98, 0x34800
	v_add_u32_e32 v240, s100, v234
	global_load_lds_dwordx4 v240, s[74:75]
	s_add_i32 m0, s99, 0xc00
	s_add_i32 s100, s98, 0x4ec00
	v_add_u32_e32 v240, s100, v235
	global_load_lds_dwordx4 v240, s[74:75]
	ds_read2_b32 v[220:221], v226 offset1:1
	s_waitcnt lgkmcnt(0)
	v_add_f32_e32 v219, v64, v220
	v_mfma_f32_32x32x16_bf16 v[48:63], v[132:135], v[214:217], v[48:63]
	v_add_f32_e32 v218, v65, v221
	v_max3_f32 v64, v219, s2, v218
	v_mfma_f32_32x32x16_bf16 v[32:47], v[128:131], v[214:217], v[32:47]
	ds_read2_b32 v[214:215], v226 offset0:2 offset1:3
	ds_read2_b32 v[222:223], v226 offset0:4 offset1:5
	ds_read2_b32 v[224:225], v226 offset0:6 offset1:7
	s_waitcnt lgkmcnt(2)
	v_add_f32_e32 v216, v66, v214
	v_add_f32_e32 v215, v67, v215
	v_max3_f32 v64, v64, v216, v215
	s_waitcnt lgkmcnt(1)
	v_add_f32_e32 v214, v68, v222
	v_add_f32_e32 v197, v69, v223
	v_max3_f32 v66, v64, v214, v197
	ds_read2_b32 v[64:65], v226 offset0:16 offset1:17
	s_waitcnt lgkmcnt(1)
	v_add_f32_e32 v69, v70, v224
	v_add_f32_e32 v68, v71, v225
	v_max3_f32 v70, v66, v69, v68
	ds_read2_b32 v[66:67], v226 offset0:18 offset1:19
	ds_read2_b32 v[220:221], v226 offset0:20 offset1:21
	ds_read2_b32 v[222:223], v226 offset0:22 offset1:23
	s_waitcnt lgkmcnt(3)
	v_add_f32_e32 v217, v72, v64
	v_add_f32_e32 v72, v73, v65
	v_max3_f32 v64, v70, v217, v72
	s_waitcnt lgkmcnt(2)
	v_add_f32_e32 v71, v74, v66
	v_add_f32_e32 v70, v75, v67
	v_max3_f32 v64, v64, v71, v70
	s_waitcnt lgkmcnt(1)
	v_add_f32_e32 v67, v76, v220
	v_add_f32_e32 v65, v77, v221
	v_max3_f32 v73, v64, v67, v65
	s_waitcnt lgkmcnt(0)
	v_add_f32_e32 v66, v78, v222
	v_add_f32_e32 v64, v79, v223
	v_max3_f32 v73, v73, v66, v64
	v_mov_b32_e32 v74, v73
	s_nop 1
	v_permlane32_swap_b32_e32 v73, v74
	v_max_f32_e32 v74, v74, v74
	v_max_f32_e32 v73, v73, v73
	v_max_f32_e32 v73, v73, v74
	v_cmp_gt_f32_e32 vcc, v73, v191
	s_cbranch_vccz .LBB0_672
	v_max_f32_e32 v73, v73, v73
	v_max_f32_e32 v74, v191, v191
	v_max_f32_e32 v73, v74, v73
	v_sub_f32_e32 v74, v191, v73
	v_exp_f32_e32 v74, v74
	v_mov_b32_e32 v191, v73
	v_mul_f32_e32 v190, v190, v74
	v_pk_mul_f32 v[30:31], v[30:31], v[74:75] op_sel_hi:[1,0]
	v_pk_mul_f32 v[28:29], v[28:29], v[74:75] op_sel_hi:[1,0]
	v_pk_mul_f32 v[26:27], v[26:27], v[74:75] op_sel_hi:[1,0]
	v_pk_mul_f32 v[24:25], v[24:25], v[74:75] op_sel_hi:[1,0]
	v_pk_mul_f32 v[22:23], v[22:23], v[74:75] op_sel_hi:[1,0]
	v_pk_mul_f32 v[20:21], v[20:21], v[74:75] op_sel_hi:[1,0]
	v_pk_mul_f32 v[18:19], v[18:19], v[74:75] op_sel_hi:[1,0]
	v_pk_mul_f32 v[16:17], v[16:17], v[74:75] op_sel_hi:[1,0]
	v_pk_mul_f32 v[14:15], v[14:15], v[74:75] op_sel_hi:[1,0]
	v_pk_mul_f32 v[12:13], v[12:13], v[74:75] op_sel_hi:[1,0]
	v_pk_mul_f32 v[10:11], v[10:11], v[74:75] op_sel_hi:[1,0]
	v_pk_mul_f32 v[8:9], v[8:9], v[74:75] op_sel_hi:[1,0]
	v_pk_mul_f32 v[6:7], v[6:7], v[74:75] op_sel_hi:[1,0]
	v_pk_mul_f32 v[4:5], v[4:5], v[74:75] op_sel_hi:[1,0]
	v_pk_mul_f32 v[2:3], v[2:3], v[74:75] op_sel_hi:[1,0]
	v_pk_mul_f32 v[0:1], v[0:1], v[74:75] op_sel_hi:[1,0]
	s_branch .LBB0_672
